# GEMM phases: phase-start stagger sleeps removed (s_sleep 85 -> s_nop)
# speedup vs baseline: 1.0125x; 1.0013x over previous
.LBB0_149:
	s_add_i32 s6, s6, -1
	s_cmp_eq_u32 s6, 0
	s_nop 0
	s_cbranch_scc0 .LBB0_149

.LBB0_224:
	s_add_i32 s2, s2, -1
	s_cmp_eq_u32 s2, 0
	s_nop 0
	s_cbranch_scc0 .LBB0_224
